# P3 loader threads take their chunk pieces in a permuted order so each loader wave runs at most 2 (one wave 0) exec-masked exp blocks per chunk instead of 6
# baseline (speedup 1.0000x reference)
; #define LAS __attribute__((address_space(3)))
; __device__ __forceinline__ void rwkv_scan_prompt(const Params& p, LAS unsigned char* lds, int bh, int rq) {
;     ...
;     const int tid = threadIdx.x, lane = tid & 63, wave = tid >> 6;
;     const int b = bh >> 3, h = bh & 7, rowbase = b * SEQ;
;     const h16* OPSG = (const h16*)(ws + OFF_OPS16);
;     const float* RKS = (const float*)(ws + OFF_RKS);
;     float* YRAW = (float*)(ws + OFF_YRAW);
;     const int rr = lane >> 4, cg_ = lane & 15, rloc = (wave & 3) * 4 + rr;
;     const int ltid = tid - 256;
;     f32x4 S = {0.f, 0.f, 0.f, 0.f};
;     h16x8 pre[NPIECE]; float prk = 0.f;
;     auto issue_chunk = [&](int c) {
; #pragma unroll
;         for (int i = 0; i < NPIECE; ++i) {
;             const int piece = ltid + 256 * i, tk = piece / 48, q = piece % 48, vec = q >> 3, c8 = q & 7;
;             pre[i] = *(const h16x8*)(OPSG + (((size_t)(rowbase + c * TC + tk) * 8 + h) * 6 + vec) * 64 + c8 * 8);
;         }
;         if (ltid < TC) prk = RKS[(size_t)(rowbase + c * TC + ltid) * 8 + h];
;     };
;     auto store_chunk = [&](int buf) {
; #pragma unroll
;         for (int i = 0; i < NPIECE; ++i) {
;             const int piece = ltid + 256 * i, tk = piece / 48, q = piece % 48, vec = q >> 3, c8 = q & 7;
;             const h16x8 v = pre[i];
;             f32x4 a, bb;
; #pragma unroll
;             for (int j = 0; j < 4; ++j) { a[j] = (float)v[j]; bb[j] = (float)v[4 + j]; }
;             if (vec == 1) {
; #pragma unroll
;                 for (int j = 0; j < 4; ++j) { a[j] = __expf(a[j]); bb[j] = __expf(bb[j]); }
;             }
;             LAS float* d = OPS + ((buf * TC + tk) * 6 + vec) * 64 + c8 * 8;
;             *(LAS f32x4*)d = a; *(LAS f32x4*)(d + 4) = bb;
;         }
;         if (ltid < TC) RKB[buf * TC + ltid] = prk;
;     };
.LBB0_308:
	s_or_b64 exec, exec, s[0:1]
	s_cmpk_lt_i32 s2, 0x100
	s_movk_i32 s0, 0x100
	s_cselect_b64 s[76:77], -1, 0
	s_cmpk_gt_i32 s2, 0xff
	v_lshlrev_b32_e32 v36, 2, v131
	v_cmp_eq_u32_e64 s[4:5], 15, v131
	v_cmp_eq_u32_e64 s[6:7], 0, v131
	v_cmp_eq_u32_e64 s[8:9], 1, v131
	v_cmp_eq_u32_e64 s[10:11], 2, v131
	v_cmp_eq_u32_e64 s[12:13], 3, v131
	v_cmp_eq_u32_e64 s[14:15], 4, v131
	v_cmp_eq_u32_e64 s[16:17], 5, v131
	v_cmp_eq_u32_e64 s[18:19], 6, v131
	v_cmp_eq_u32_e64 s[20:21], 7, v131
	v_cmp_eq_u32_e64 s[22:23], 8, v131
	v_cmp_eq_u32_e64 s[24:25], 9, v131
	v_cmp_eq_u32_e64 s[26:27], 10, v131
	v_cmp_eq_u32_e64 s[28:29], 11, v131
	v_cmp_eq_u32_e64 s[30:31], 12, v131
	v_cmp_eq_u32_e64 s[34:35], 13, v131
	v_cmp_eq_u32_e64 s[36:37], 14, v131
	v_lshlrev_b32_e32 v52, 4, v131
	s_barrier
	s_cbranch_scc1 .LBB0_360
	v_mov_b32_e32 v222, v132
	v_subrev_u32_e32 v0, 0x100, v132
	v_lshrrev_b32_e32 v1, 6, v0
	v_and_b32_e32 v2, 63, v0
	v_and_b32_e32 v3, 7, v2
	v_lshrrev_b32_e32 v4, 3, v2
	v_mul_u32_u24_e32 v5, 48, v4
	v_lshl_add_u32 v5, v1, 4, v5
	v_add3_u32 v5, v5, v3, 8
	v_subrev_u32_e32 v6, 48, v2
	v_subrev_u32_e32 v7, 24, v2
	v_cmp_eq_u32_e32 vcc, 1, v1
	s_nop 1
	v_cndmask_b32_e32 v6, v6, v7, vcc
	v_cmp_eq_u32_e32 vcc, 2, v1
	s_nop 1
	v_cndmask_b32_e32 v6, v6, v2, vcc
	v_add_u32_e32 v7, 64, v2
	v_cmp_eq_u32_e32 vcc, 3, v1
	s_nop 1
	v_cndmask_b32_e32 v6, v6, v7, vcc
	v_lshrrev_b32_e32 v7, 3, v6
	v_mul_u32_u24_e32 v4, 0xab, v7
	v_lshrrev_b32_e32 v4, 9, v4
	v_mul_u32_u24_e32 v3, 3, v4
	v_sub_u32_e32 v7, v7, v3
	v_mul_u32_u24_e32 v4, 48, v4
	v_lshl_add_u32 v4, v7, 4, v4
	v_and_b32_e32 v6, 7, v6
	v_add_u32_e32 v4, v4, v6
	v_cmp_eq_u32_e32 vcc, 0, v1
	s_nop 1
	v_cndmask_b32_e64 v6, 40, 48, vcc
	v_cmp_gt_u32_e64 s[98:99], 3, v1
	v_cmp_lt_u32_e32 vcc, v2, v6
	s_nop 1
	s_and_b64 vcc, vcc, s[98:99]
	s_nop 1
	v_cndmask_b32_e32 v4, v4, v5, vcc
	v_add_u32_e32 v4, 0x100, v4
	v_cmp_lt_u32_e32 vcc, 0xff, v132
	s_nop 1
	v_cndmask_b32_e32 v132, v132, v4, vcc
	v_add_u16_e32 v3, 0x100, v132
	v_mul_u32_u24_e32 v4, 0x556, v3
	v_lshrrev_b32_e32 v57, 16, v4
	v_mul_lo_u16_e32 v4, 48, v57
	v_sub_u16_e32 v63, v3, v4
	v_lshlrev_b32_e32 v3, 3, v63
	v_and_b32_e32 v46, 56, v3
	v_add_u16_e32 v3, 0x200, v132
	v_mul_u32_u24_e32 v4, 0x556, v3
	v_lshrrev_b32_e32 v65, 16, v4
	v_subrev_co_u32_e32 v37, vcc, 0x100, v132
	v_cmp_gt_u32_e64 s[38:39], s0, v132
	s_mov_b32 s0, 0xaaab
	v_mul_lo_u16_e32 v4, 48, v65
	v_mul_u32_u24_sdwa v1, v37, s0 dst_sel:DWORD dst_unused:UNUSED_PAD src0_sel:WORD_0 src1_sel:DWORD
	v_sub_u16_e32 v67, v3, v4
	v_lshrrev_b32_e32 v47, 21, v1
	v_mul_u32_u24_e32 v2, 0x556, v132
	v_lshlrev_b32_e32 v3, 3, v67
	v_mul_lo_u16_e32 v1, 48, v47
	v_lshrrev_b32_e32 v51, 16, v2
	v_and_b32_e32 v50, 56, v3
	v_add_u16_e32 v3, 0x300, v132
	v_sub_u16_e32 v1, v37, v1
	v_mul_lo_u16_e32 v2, 48, v51
	v_mul_u32_u24_e32 v4, 0x556, v3
	v_lshrrev_b32_e32 v38, 3, v1
	v_lshlrev_b32_e32 v1, 3, v1
	v_sub_u16_e32 v2, v132, v2
	v_lshrrev_b32_e32 v108, 16, v4
	v_and_b32_e32 v1, 56, v1
	v_lshrrev_b32_e32 v42, 3, v2
	v_lshlrev_b32_e32 v2, 3, v2
	v_mul_lo_u16_e32 v4, 48, v108
	v_mul_u32_u24_e32 v5, 6, v47
	v_and_b32_e32 v2, 56, v2
	v_sub_u16_e32 v109, v3, v4
	v_add_lshl_u32 v5, v5, v38, 8
	v_lshlrev_b32_e32 v6, 2, v1
	s_movk_i32 s0, 0x556
	v_lshlrev_b32_e32 v3, 3, v109
	v_or_b32_e32 v4, 0x400, v132
	v_add3_u32 v111, 0, v5, v6
	v_mad_u32_u24 v5, v51, 6, v42
	v_lshl_add_u32 v112, v2, 2, 0
	v_lshrrev_b32_e32 v44, 3, v63
	v_and_b32_e32 v56, 56, v3
	v_mul_u32_u24_sdwa v3, v4, s0 dst_sel:DWORD dst_unused:UNUSED_PAD src0_sel:WORD_0 src1_sel:DWORD
	v_lshl_add_u32 v113, v5, 8, v112
	v_mul_u32_u24_e32 v5, 6, v57
	v_lshrrev_b32_e32 v110, 16, v3
	v_add_lshl_u32 v5, v5, v44, 8
	v_lshlrev_b32_e32 v6, 2, v46
	v_lshrrev_b32_e32 v48, 3, v67
	v_mul_lo_u16_e32 v3, 48, v110
	v_add3_u32 v114, 0, v5, v6
	v_mul_u32_u24_e32 v5, 6, v65
	v_sub_u16_e32 v3, v4, v3
	v_add_lshl_u32 v5, v5, v48, 8
	v_lshlrev_b32_e32 v6, 2, v50
	v_lshrrev_b32_e32 v54, 3, v109
	v_lshrrev_b32_e32 v58, 3, v3
	v_lshlrev_b32_e32 v3, 3, v3
	v_add3_u32 v115, 0, v5, v6
	v_mul_u32_u24_e32 v5, 6, v108
; #define LAS __attribute__((address_space(3)))
; __device__ __forceinline__ void rwkv_scan_prompt(const Params& p, LAS unsigned char* lds, int bh, int rq) {
;     ...
;     const int rr = lane >> 4, cg_ = lane & 15, rloc = (wave & 3) * 4 + rr;
;     const int ltid = tid - 256;
;     f32x4 S = {0.f, 0.f, 0.f, 0.f};
;     h16x8 pre[NPIECE]; float prk = 0.f;
;     auto issue_chunk = [&](int c) {
; #pragma unroll
;         for (int i = 0; i < NPIECE; ++i) {
;             const int piece = ltid + 256 * i, tk = piece / 48, q = piece % 48, vec = q >> 3, c8 = q & 7;
;             pre[i] = *(const h16x8*)(OPSG + (((size_t)(rowbase + c * TC + tk) * 8 + h) * 6 + vec) * 64 + c8 * 8);
;         }
;         if (ltid < TC) prk = RKS[(size_t)(rowbase + c * TC + ltid) * 8 + h];
;     };
;     auto store_chunk = [&](int buf) {
; #pragma unroll
;         for (int i = 0; i < NPIECE; ++i) {
;             const int piece = ltid + 256 * i, tk = piece / 48, q = piece % 48, vec = q >> 3, c8 = q & 7;
;             const h16x8 v = pre[i];
;             f32x4 a, bb;
; #pragma unroll
;             for (int j = 0; j < 4; ++j) { a[j] = (float)v[j]; bb[j] = (float)v[4 + j]; }
;             if (vec == 1) {
; #pragma unroll
;                 for (int j = 0; j < 4; ++j) { a[j] = __expf(a[j]); bb[j] = __expf(bb[j]); }
;             }
;             LAS float* d = OPS + ((buf * TC + tk) * 6 + vec) * 64 + c8 * 8;
;             *(LAS f32x4*)d = a; *(LAS f32x4*)(d + 4) = bb;
;         }
;         if (ltid < TC) RKB[buf * TC + ltid] = prk;
;     };
;     if (wave >= 4) { issue_chunk(0); store_chunk(0); issue_chunk(1); }
	v_and_b32_e32 v3, 56, v3
	v_add_lshl_u32 v5, v5, v54, 8
	v_lshlrev_b32_e32 v6, 2, v56
	v_add3_u32 v116, 0, v5, v6
	v_mad_u32_u24 v5, v110, 6, v58
	v_lshl_add_u32 v117, v3, 2, 0
	v_lshl_add_u32 v118, v5, 8, v117
	v_mul_i32_i24_e32 v5, 0x2aab, v37
	v_mov_b32_e32 v6, 3
	v_ashrrev_i16_sdwa v7, v6, v5 dst_sel:DWORD dst_unused:UNUSED_PAD src0_sel:DWORD src1_sel:WORD_1
	v_lshrrev_b32_e32 v5, 31, v5
	v_add_u16_e32 v127, v7, v5
	v_mul_lo_u16_e32 v5, 48, v127
	v_sub_u16_e32 v5, v37, v5
	v_ashrrev_i32_sdwa v60, v6, sext(v5) dst_sel:DWORD dst_unused:UNUSED_PAD src0_sel:DWORD src1_sel:WORD_0
	v_lshlrev_b32_sdwa v5, v6, sext(v5) dst_sel:DWORD dst_unused:UNUSED_PAD src0_sel:DWORD src1_sel:WORD_0
	v_or_b32_e32 v6, 0x100, v132
	v_mul_u32_u24_sdwa v7, v6, s0 dst_sel:DWORD dst_unused:UNUSED_PAD src0_sel:WORD_0 src1_sel:DWORD
	v_lshrrev_b32_e32 v137, 16, v7
	v_mul_lo_u16_e32 v7, 48, v137
	v_sub_u16_e32 v139, v6, v7
	v_lshlrev_b32_e32 v6, 3, v139
	v_and_b32_e32 v62, 56, v6
	v_or_b32_e32 v6, 0x200, v132
	v_mul_u32_u24_sdwa v7, v6, s0 dst_sel:DWORD dst_unused:UNUSED_PAD src0_sel:WORD_0 src1_sel:DWORD
	v_lshrrev_b32_e32 v141, 16, v7
	v_mul_lo_u16_e32 v7, 48, v141
	v_sub_u16_e32 v143, v6, v7
	v_mov_b32_e32 v41, 0
	v_lshlrev_b32_e32 v6, 3, v143
	v_lshlrev_b32_e32 v40, 1, v1
	v_and_b32_e32 v64, 56, v6
	v_or_b32_e32 v6, 0x300, v132
	v_lshl_add_u64 v[68:69], s[86:87], 0, v[40:41]
	v_lshlrev_b32_e32 v40, 1, v2
	v_mul_u32_u24_sdwa v7, v6, s0 dst_sel:DWORD dst_unused:UNUSED_PAD src0_sel:WORD_0 src1_sel:DWORD
	v_lshl_add_u64 v[70:71], s[86:87], 0, v[40:41]
	v_lshlrev_b32_e32 v40, 1, v46
	v_lshrrev_b32_e32 v145, 16, v7
	v_lshl_add_u64 v[72:73], s[86:87], 0, v[40:41]
	v_lshlrev_b32_e32 v40, 1, v50
	v_mul_lo_u16_e32 v7, 48, v145
	v_lshl_add_u64 v[74:75], s[86:87], 0, v[40:41]
	v_lshlrev_b32_e32 v40, 1, v56
	v_readlane_b32 s60, v253, 20
	s_mov_b32 s0, 0x5555556
	s_add_i32 s3, 0, 0x18000
	v_and_b32_e32 v5, 56, v5
	v_sub_u16_e32 v147, v6, v7
	v_lshl_add_u64 v[76:77], s[86:87], 0, v[40:41]
	v_lshlrev_b32_e32 v40, 1, v3
	v_mov_b32_e32 v53, v41
	v_readlane_b32 s74, v253, 34
	v_readlane_b32 s75, v253, 35
	v_mul_hi_u32 v1, v4, s0
	v_bfe_u32 v0, v132, 4, 4
	v_lshl_add_u32 v119, v37, 2, s3
	v_add_u32_e32 v126, s3, v36
	s_movk_i32 s3, 0x120
	v_lshlrev_b32_e32 v6, 3, v147
	s_add_u32 s84, s82, 0x1aec800
	v_lshl_add_u64 v[78:79], s[86:87], 0, v[40:41]
	v_lshlrev_b32_e32 v40, 1, v5
	v_lshl_add_u64 v[2:3], s[74:75], 0, v[52:53]
	s_mov_b64 s[58:59], 0x419c100
	v_or_b32_e32 v148, 64, v1
	v_mov_b32_e32 v1, 64
	v_mov_b32_e32 v39, v41
	v_mov_b32_e32 v43, v41
	v_mov_b32_e32 v45, v41
	v_mov_b32_e32 v49, v41
	v_mov_b32_e32 v55, v41
	v_mov_b32_e32 v59, v41
	v_cmp_gt_u32_e64 s[40:41], 32, v37
	v_cmp_ne_u32_e64 s[42:43], 1, v38
	s_mov_b32 s1, 0
	v_cmp_ne_u32_e64 s[44:45], 1, v42
	v_cmp_ne_u32_e64 s[46:47], 1, v44
	v_cmp_ne_u32_e64 s[48:49], 1, v48
	v_cmp_ne_u32_e64 s[50:51], 1, v54
	v_cmp_ne_u32_e64 s[52:53], 1, v58
	v_add_u32_e32 v120, 32, v47
	v_add_u32_e32 v121, 32, v57
	v_add_u32_e32 v122, 32, v65
	v_add_u32_e32 v123, 32, v108
	v_add_u32_e32 v124, 32, v110
	v_add_u32_e32 v125, 0xffffff20, v132
	v_cmp_ne_u32_e64 s[54:55], 1, v60
	v_lshl_add_u32 v129, v5, 2, 0
	v_cmp_gt_u32_e64 s[56:57], s3, v132
	v_ashrrev_i32_e32 v61, 31, v60
	v_mul_u32_u24_e32 v135, 0x600, v131
	v_and_b32_e32 v66, 56, v6
	s_addc_u32 s85, s83, 0
	v_lshl_add_u64 v[80:81], s[86:87], 0, v[40:41]
	v_lshl_add_u64 v[82:83], v[2:3], 0, s[58:59]
	v_add_u32_e32 v53, 0xffffff40, v132
	v_or_b32_e32 v149, 64, v51
	v_add_u32_sdwa v150, sext(v127), v1 dst_sel:DWORD dst_unused:UNUSED_PAD src0_sel:WORD_0 src1_sel:DWORD
	v_lshlrev_b32_e32 v84, 2, v0
	s_mov_b32 s3, s2
	v_readlane_b32 s61, v253, 21
	v_readlane_b32 s62, v253, 22
	v_readlane_b32 s63, v253, 23
	v_readlane_b32 s64, v253, 24
	v_readlane_b32 s65, v253, 25
	v_readlane_b32 s66, v253, 26
	v_readlane_b32 s67, v253, 27
	v_readlane_b32 s68, v253, 28
	v_readlane_b32 s69, v253, 29
	v_readlane_b32 s70, v253, 30
	v_readlane_b32 s71, v253, 31
	v_readlane_b32 s72, v253, 32
	v_readlane_b32 s73, v253, 33
	v_mov_b32_e32 v132, v222
	s_branch .LBB0_311
